# recurrence producer loop: 64-bit VALU address arithmetic for the 14 prefetch loads replaced by scalar-unit bases + SGPR-base/VGPR-offset loads (S=5)
# baseline (speedup 1.0000x reference)
; #define LAS __attribute__((address_space(3)))
; __device__ __forceinline__ void delta_pre_load(int b, int h, int c, int pt, DeltaPre& dp) {
;     const int bh = b * 8 + h, tt = pt >> 3, d0 = (pt & 7) * 16; const size_t t = (size_t)bh * SEQ + c * 32 + tt;
;     const size_t ro = ((size_t)b * SEQ + c * 32 + tt) * D + h * 128 + d0;
;     const bf16* Kt = (const bf16*)(karg_ws() + WS_Z + 3 * ZB) + ro; const bf16* Qt = (const bf16*)(karg_ws() + WS_H) + ro; const bf16* Vt = (const bf16*)(karg_ws() + WS_Z + 4 * ZB) + ro;
;     dp.k0 = *(const u32x4*)Kt; dp.k1 = *(const u32x4*)(Kt + 8); dp.q0 = *(const u32x4*)Qt; dp.q1 = *(const u32x4*)(Qt + 8); dp.v0 = *(const u32x4*)Vt; dp.v1 = *(const u32x4*)(Vt + 8);
;     const float* GC = (const float*)(karg_ws() + WS_GC);
;     dp.gct = GC[t]; dp.gl = GC[(size_t)bh * SEQ + c * 32 + 31]; dp.bet = ((const float*)(karg_ws() + WS_BETA))[t];
;     dp.nk = ((const float*)((const unsigned char*)karg_out() + OSB_NK))[t]; dp.nq = ((const float*)((const unsigned char*)karg_out() + OSB_NQ))[t];
;     dp.tia = *(const u32x4*)((const bf16*)(karg_ws() + (pt < 128 ? WS_TINV : WS_ATT)) + ((size_t)bh * 64 + c) * 1024 + (pt & 127) * 8);
; }
; __device__ __forceinline__ void delta_rec_stage(LAS unsigned char* buf, int pt, const DeltaPre& dp) {
;     const int tt = pt >> 3, dg = pt & 7, d0 = dg * 16;
;     { LAS bf16* dst = (LAS bf16*)(buf + (pt < 128 ? DR_TI : DR_AT)) + ((pt & 127) >> 2) * 40 + (pt & 3) * 8; *(LAS u32x4*)dst = dp.tia; }
;     if (pt == 0) *(LAS float*)(buf + DR_EGL) = __expf(dp.gl);
;     const float eg = __expf(dp.gct), ekd = __expf(dp.gl - dp.gct);
;     const float fq = dp.nq * eg, fkb = dp.nk * dp.bet * eg, fkd = dp.nk * ekd, bet = dp.bet;
;     float k[16], q[16], v[16];
;     unpack8(dp.k0, k); unpack8(dp.k1, k + 8); unpack8(dp.q0, q); unpack8(dp.q1, q + 8); unpack8(dp.v0, v); unpack8(dp.v1, v + 8);
;     LAS bf16* KB = (LAS bf16*)(buf + DR_KB) + tt * 136 + d0; LAS bf16* QD = (LAS bf16*)(buf + DR_QD) + tt * 136 + d0;
;     *(LAS bf16x8*)KB = pack8(k[0] * fkb, k[1] * fkb, k[2] * fkb, k[3] * fkb, k[8] * fkb, k[9] * fkb, k[10] * fkb, k[11] * fkb);
;     *(LAS bf16x8*)(KB + 8) = pack8(k[4] * fkb, k[5] * fkb, k[6] * fkb, k[7] * fkb, k[12] * fkb, k[13] * fkb, k[14] * fkb, k[15] * fkb);
;     *(LAS bf16x8*)QD = pack8(q[0] * fq, q[1] * fq, q[2] * fq, q[3] * fq, q[8] * fq, q[9] * fq, q[10] * fq, q[11] * fq);
.LBB0_1838:
	v_lshl_add_u64 v[78:79], v[76:77], 0, s[12:13]
	s_add_u32 s46, s76, s12
	s_addc_u32 s47, s77, s13
	s_add_u32 s48, s46, 0xb130000
	s_addc_u32 s49, s47, 0
	s_add_u32 s50, s46, 0x3030000
	s_addc_u32 s51, s47, 0
	s_add_u32 s52, s46, 0xd170000
	s_addc_u32 s53, s47, 0
	s_add_u32 s54, s76, s4
	s_addc_u32 s55, s77, s5
	s_add_u32 s60, s54, 0x2880000
	s_addc_u32 s61, s55, 0
	s_add_u32 s62, s54, s28
	s_addc_u32 s63, s55, 0
	s_add_u32 s56, s44, s4
	s_addc_u32 s57, s45, s5
	s_add_u32 s64, s56, s29
	s_addc_u32 s65, s57, 0
	s_add_u32 s66, s56, s30
	s_addc_u32 s67, s57, 0
	s_lshr_b64 s[58:59], s[12:13], 5
	s_add_u32 s58, s58, s76
	s_addc_u32 s59, s59, s77
	s_waitcnt vmcnt(2)
	v_mov_b64_e32 v[130:131], v[2:3]
	v_mov_b64_e32 v[128:129], v[0:1]
	global_load_dwordx4 v[64:67], v72, s[48:49]
	global_load_dwordx4 v[60:63], v72, s[48:49] offset:16
	global_load_dwordx4 v[56:59], v72, s[50:51]
	global_load_dwordx4 v[52:55], v72, s[50:51] offset:16
	global_load_dwordx4 v[40:43], v72, s[52:53]
	global_load_dwordx4 v[32:35], v72, s[52:53] offset:16
	global_load_dword v84, v74, s[60:61] offset:384
	global_load_dword v85, v69, s[54:55] offset:508
	global_load_dword v68, v74, s[62:63] offset:384
	global_load_dword v86, v74, s[64:65] offset:384
	global_load_dword v87, v74, s[66:67] offset:384
	global_load_dwordx4 v[0:3], v70, s[58:59]
	v_lshl_add_u64 v[20:21], v[78:79], 0, s[22:23]
	global_load_dwordx4 v[24:27], v[20:21], off
	global_load_dwordx4 v[20:23], v[20:21], off offset:16
	s_bitcmp1_b32 s36, 0
	s_cselect_b32 s26, 0xc210, 0
	s_add_i32 s37, s26, 0
	v_add_u32_e32 v110, s37, v115
	v_add3_u32 v110, v110, v121, v122
	ds_write_b128 v110, v[128:131]
	s_and_saveexec_b64 s[26:27], s[10:11]
	s_cbranch_execz .LBB0_1840
	v_mul_f32_e32 v110, 0x3fb8aa3b, v124
	v_exp_f32_e32 v110, v110
	v_mov_b32_e32 v117, s37
	ds_write_b32 v117, v110 offset:49664
.LBB0_1840:
	s_or_b64 exec, exec, s[26:27]
	v_mul_f32_e32 v110, 0x3fb8aa3b, v123
	v_exp_f32_e32 v117, v110
	v_sub_f32_e32 v110, v124, v123
	v_mul_f32_e32 v110, 0x3fb8aa3b, v110
	v_exp_f32_e32 v119, v110
	v_mul_f32_e32 v118, v116, v125
	v_mul_f32_e32 v118, v117, v118
	v_lshlrev_b32_e32 v128, 16, v48
	v_and_b32_e32 v129, 0xffff0000, v48
	v_lshlrev_b32_e32 v48, 16, v49
	v_and_b32_e32 v49, 0xffff0000, v49
	v_lshlrev_b32_e32 v130, 16, v44
	v_and_b32_e32 v131, 0xffff0000, v44
	v_lshlrev_b32_e32 v134, 16, v45
	v_and_b32_e32 v135, 0xffff0000, v45
	v_mul_f32_e32 v110, v117, v126
	v_mul_f32_e32 v117, v125, v119
	v_pk_mul_f32 v[124:125], v[118:119], v[128:129] op_sel_hi:[0,1]
	v_pk_mul_f32 v[126:127], v[118:119], v[48:49] op_sel_hi:[0,1]
	v_pk_mul_f32 v[132:133], v[118:119], v[130:131] op_sel_hi:[0,1]
	v_pk_mul_f32 v[44:45], v[118:119], v[134:135] op_sel_hi:[0,1]
	v_add3_u32 v120, s37, v91, v114
	v_cvt_pk_bf16_f32 v124, v124, v125
	v_cvt_pk_bf16_f32 v125, v126, v127
	v_cvt_pk_bf16_f32 v126, v132, v133
	v_cvt_pk_bf16_f32 v127, v44, v45
	ds_write_b128 v120, v[124:127]
	v_lshlrev_b32_e32 v124, 16, v50
	v_and_b32_e32 v125, 0xffff0000, v50
	v_lshlrev_b32_e32 v50, 16, v51
	v_and_b32_e32 v51, 0xffff0000, v51
	v_lshlrev_b32_e32 v132, 16, v46
	v_and_b32_e32 v133, 0xffff0000, v46
	v_lshlrev_b32_e32 v138, 16, v47
	v_and_b32_e32 v139, 0xffff0000, v47
	v_pk_mul_f32 v[44:45], v[118:119], v[124:125] op_sel_hi:[0,1]
	v_pk_mul_f32 v[126:127], v[118:119], v[50:51] op_sel_hi:[0,1]
	v_pk_mul_f32 v[136:137], v[118:119], v[132:133] op_sel_hi:[0,1]
	v_pk_mul_f32 v[118:119], v[118:119], v[138:139] op_sel_hi:[0,1]
	v_cvt_pk_bf16_f32 v44, v44, v45
	v_cvt_pk_bf16_f32 v45, v126, v127
	v_cvt_pk_bf16_f32 v46, v136, v137
	v_cvt_pk_bf16_f32 v47, v118, v119
	ds_write_b128 v120, v[44:47] offset:16
	v_lshlrev_b32_e32 v44, 16, v36
	v_and_b32_e32 v45, 0xffff0000, v36
	v_lshlrev_b32_e32 v36, 16, v37
	v_and_b32_e32 v37, 0xffff0000, v37
	v_lshlrev_b32_e32 v46, 16, v28
	v_and_b32_e32 v47, 0xffff0000, v28
	v_lshlrev_b32_e32 v28, 16, v29
	v_and_b32_e32 v29, 0xffff0000, v29
	v_pk_mul_f32 v[44:45], v[110:111], v[44:45] op_sel_hi:[0,1]
	v_pk_mul_f32 v[36:37], v[110:111], v[36:37] op_sel_hi:[0,1]
	v_pk_mul_f32 v[46:47], v[110:111], v[46:47] op_sel_hi:[0,1]
	v_pk_mul_f32 v[28:29], v[110:111], v[28:29] op_sel_hi:[0,1]
	v_cvt_pk_bf16_f32 v44, v44, v45
	v_cvt_pk_bf16_f32 v45, v36, v37
	v_cvt_pk_bf16_f32 v46, v46, v47
	v_cvt_pk_bf16_f32 v47, v28, v29
	v_lshlrev_b32_e32 v28, 16, v38
	v_and_b32_e32 v29, 0xffff0000, v38
	v_lshlrev_b32_e32 v36, 16, v39
	v_and_b32_e32 v37, 0xffff0000, v39
	v_lshlrev_b32_e32 v38, 16, v30
	v_and_b32_e32 v39, 0xffff0000, v30
	v_lshlrev_b32_e32 v30, 16, v31
	v_and_b32_e32 v31, 0xffff0000, v31
	ds_write_b128 v120, v[44:47] offset:8704
	v_pk_mul_f32 v[28:29], v[110:111], v[28:29] op_sel_hi:[0,1]
	v_pk_mul_f32 v[36:37], v[110:111], v[36:37] op_sel_hi:[0,1]
	v_pk_mul_f32 v[38:39], v[110:111], v[38:39] op_sel_hi:[0,1]
	v_pk_mul_f32 v[44:45], v[110:111], v[30:31] op_sel_hi:[0,1]
	v_cvt_pk_bf16_f32 v28, v28, v29
	v_cvt_pk_bf16_f32 v29, v36, v37
	v_cvt_pk_bf16_f32 v30, v38, v39
	v_cvt_pk_bf16_f32 v31, v44, v45
	ds_write_b128 v120, v[28:31] offset:8720
	v_add3_u32 v28, s37, v90, v80
	v_add3_u32 v28, v28, v81, v82
	v_add_u32_e32 v232, v28, v230
	v_pk_mul_f32 v[190:191], v[116:117], v[128:129] op_sel:[1,0]
	v_pk_mul_f32 v[192:193], v[116:117], v[48:49] op_sel:[1,0]
	v_pk_mul_f32 v[194:195], v[116:117], v[124:125] op_sel:[1,0]
	v_pk_mul_f32 v[196:197], v[116:117], v[50:51] op_sel:[1,0]
	v_pk_mul_f32 v[198:199], v[116:117], v[130:131] op_sel:[1,0]
	v_pk_mul_f32 v[200:201], v[116:117], v[134:135] op_sel:[1,0]
	v_pk_mul_f32 v[202:203], v[116:117], v[132:133] op_sel:[1,0]
	v_pk_mul_f32 v[204:205], v[116:117], v[138:139] op_sel:[1,0]
	v_cvt_pk_bf16_f32 v206, v190, v191
; #define LAS __attribute__((address_space(3)))
; __device__ __forceinline__ unsigned f2bf(float f) { return pk2(f, f) & 0xffffu; }
; __device__ __forceinline__ float rsq_f(float x) { return __builtin_amdgcn_rsqf(x); }
; __device__ __forceinline__ int perm16(int e) { return (e & ~12) | ((e >> 1) & 4) | ((e << 1) & 8); }
; __device__ __forceinline__ void delta_rec_stage(LAS unsigned char* buf, int pt, const DeltaPre& dp) {
;     ...
;     LAS bf16* KDT = (LAS bf16*)(buf + DR_KDT) + d0 * 40 + perm16(tt);
; #pragma unroll
;     for (int e = 0; e < 16; ++e) KDT[e * 40] = (bf16)f2bf(k[e] * fkd);
;     LAS float* VB = (LAS float*)(buf + DR_VB) + tt * 132 + d0;
; #pragma unroll
;     for (int e4 = 0; e4 < 4; ++e4) *(LAS f32x4*)(VB + 4 * e4) = (f32x4){v[4 * e4] * bet, v[4 * e4 + 1] * bet, v[4 * e4 + 2] * bet, v[4 * e4 + 3] * bet};
; }
; __device__ __forceinline__ void delta_out_norm(const LAS float* ob, int pt, const float* dn16, const u32x4 z0, const u32x4 z1, bf16* dst) {
;     const LAS float* p = ob + (pt >> 3) * 132 + (pt & 7) * 16;
;     float o[16], z[16];
; #pragma unroll
;     for (int e4 = 0; e4 < 4; ++e4) { const f32x4 t = *(const LAS f32x4*)(p + 4 * e4); o[4 * e4] = t[0]; o[4 * e4 + 1] = t[1]; o[4 * e4 + 2] = t[2]; o[4 * e4 + 3] = t[3]; }
;     float ss = 0.f;
; #pragma unroll
;     for (int e = 0; e < 16; ++e) ss += o[e] * o[e];
;     ss = red8(ss);
;     const float rstd = rsq_f(ss * (1.f / 128.f) + EPS);
;     unpack8(z0, z); unpack8(z1, z + 8);
; #pragma unroll
;     for (int e = 0; e < 16; ++e) o[e] = o[e] * rstd * dn16[e] * z[e];
;     *(bf16x8*)dst = pack8(o[0], o[1], o[2], o[3], o[4], o[5], o[6], o[7]); *(bf16x8*)(dst + 8) = pack8(o[8], o[9], o[10], o[11], o[12], o[13], o[14], o[15]);
; __device__ __forceinline__ void delta_rec_task(const Params& P, LAS unsigned char* lds, int b, int h, int tid) {
;     ...
;         for (int c = 0; c < NC; ++c) {
;             if (c > 0) { dcur = dnxt; zc0 = zn0; zc1 = zn1; }
;             if (c + 2 < NC) delta_pre_load(b, h, c + 2, pt, dnxt);
;             zn0 = *(const u32x4*)(zgp + (size_t)c * 32 * D); zn1 = *(const u32x4*)(zgp + (size_t)c * 32 * D + 8);
;             if (c + 1 < NC) delta_rec_stage(lds + ((c + 1) & 1) * DR_BUF, pt, dcur);
;             if (c > 0) delta_out_norm((const LAS float*)(lds + DR_OB) + ((c - 1) & 1) * 32 * 132, pt, dn16, zc0, zc1, zgp + (size_t)(c - 1) * 32 * D);
;             DR_BAR();
;         }
	v_cvt_pk_bf16_f32 v207, v192, v193
	v_cvt_pk_bf16_f32 v208, v194, v195
	v_cvt_pk_bf16_f32 v209, v196, v197
	v_cvt_pk_bf16_f32 v210, v198, v199
	v_cvt_pk_bf16_f32 v211, v200, v201
	v_cvt_pk_bf16_f32 v212, v202, v203
	v_cvt_pk_bf16_f32 v213, v204, v205
	v_mov_b32_dpp v214, v206 row_ror:8 row_mask:0xf bank_mask:0xf
	v_mov_b32_dpp v215, v207 row_ror:8 row_mask:0xf bank_mask:0xf
	v_mov_b32_dpp v216, v208 row_ror:8 row_mask:0xf bank_mask:0xf
	v_mov_b32_dpp v217, v209 row_ror:8 row_mask:0xf bank_mask:0xf
	v_mov_b32_dpp v218, v210 row_ror:8 row_mask:0xf bank_mask:0xf
	v_mov_b32_dpp v219, v211 row_ror:8 row_mask:0xf bank_mask:0xf
	v_mov_b32_dpp v220, v212 row_ror:8 row_mask:0xf bank_mask:0xf
	v_mov_b32_dpp v221, v213 row_ror:8 row_mask:0xf bank_mask:0xf
	v_perm_b32 v190, v214, v206, v231
	v_perm_b32 v191, v215, v207, v231
	v_perm_b32 v192, v216, v208, v231
	v_perm_b32 v193, v217, v209, v231
	v_perm_b32 v194, v218, v210, v231
	v_perm_b32 v195, v219, v211, v231
	v_perm_b32 v196, v220, v212, v231
	v_perm_b32 v197, v221, v213, v231
	ds_write_b32 v232, v190 offset:17408
	ds_write_b32 v232, v191 offset:17568
	ds_write_b32 v232, v192 offset:17728
	ds_write_b32 v232, v193 offset:17888
	ds_write_b32 v232, v194 offset:18048
	ds_write_b32 v232, v195 offset:18208
	ds_write_b32 v232, v196 offset:18368
	ds_write_b32 v232, v197 offset:18528
	v_lshlrev_b32_e32 v28, 16, v16
	v_and_b32_e32 v29, 0xffff0000, v16
	v_lshlrev_b32_e32 v16, 16, v17
	v_and_b32_e32 v17, 0xffff0000, v17
	v_pk_mul_f32 v[30:31], v[116:117], v[16:17] op_sel_hi:[0,1]
	v_lshlrev_b32_e32 v16, 16, v18
	v_and_b32_e32 v17, 0xffff0000, v18
	v_lshlrev_b32_e32 v18, 16, v19
	v_and_b32_e32 v19, 0xffff0000, v19
	v_add3_u32 v110, s37, v88, v111
	v_pk_mul_f32 v[16:17], v[116:117], v[16:17] op_sel_hi:[0,1]
	v_pk_mul_f32 v[18:19], v[116:117], v[18:19] op_sel_hi:[0,1]
	s_and_b32 s26, s15, 32
	ds_write_b128 v110, v[16:19] offset:32784
	v_lshlrev_b32_e32 v16, 16, v12
	v_and_b32_e32 v17, 0xffff0000, v12
	v_lshlrev_b32_e32 v12, 16, v13
	v_and_b32_e32 v13, 0xffff0000, v13
	s_mulk_i32 s26, 0x210
	v_pk_mul_f32 v[16:17], v[116:117], v[16:17] op_sel_hi:[0,1]
	v_pk_mul_f32 v[18:19], v[116:117], v[12:13] op_sel_hi:[0,1]
	v_add_u32_e32 v44, s26, v89
	ds_write_b128 v110, v[16:19] offset:32800
	ds_read_b128 v[16:19], v44
	v_pk_mul_f32 v[28:29], v[116:117], v[28:29] op_sel_hi:[0,1]
	ds_write_b128 v110, v[28:31] offset:32768
	ds_read_b128 v[28:31], v44 offset:16
	ds_read_b128 v[36:39], v44 offset:32
	ds_read_b128 v[44:47], v44 offset:48
	v_lshlrev_b32_e32 v12, 16, v14
	s_waitcnt lgkmcnt(4)
	v_mul_f32_e32 v50, v17, v17
	v_fmac_f32_e32 v50, v16, v16
	v_fmac_f32_e32 v50, v18, v18
	v_fmac_f32_e32 v50, v19, v19
	s_waitcnt lgkmcnt(2)
	v_fmac_f32_e32 v50, v28, v28
	v_fmac_f32_e32 v50, v29, v29
	v_fmac_f32_e32 v50, v30, v30
	v_fmac_f32_e32 v50, v31, v31
	s_waitcnt lgkmcnt(1)
	v_fmac_f32_e32 v50, v36, v36
	v_fmac_f32_e32 v50, v37, v37
	v_pk_mul_f32 v[48:49], v[38:39], v[38:39]
	v_and_b32_e32 v13, 0xffff0000, v14
	v_lshlrev_b32_e32 v14, 16, v15
	v_and_b32_e32 v15, 0xffff0000, v15
	v_add_f32_e32 v48, v48, v50
	v_pk_mul_f32 v[12:13], v[116:117], v[12:13] op_sel_hi:[0,1]
	v_pk_mul_f32 v[14:15], v[116:117], v[14:15] op_sel_hi:[0,1]
	v_add_f32_e32 v116, v49, v48
	s_waitcnt lgkmcnt(0)
	v_pk_mul_f32 v[50:51], v[44:45], v[44:45]
	v_pk_mul_f32 v[48:49], v[46:47], v[46:47]
	v_add_f32_e32 v50, v50, v116
	v_add_f32_e32 v50, v51, v50
	v_add_f32_e32 v48, v48, v50
	v_add_f32_e32 v48, v49, v48
	ds_write_b128 v110, v[12:15] offset:32816
	v_lshlrev_b32_e32 v12, 16, v8
	v_add_f32_dpp v48, v48, v48 quad_perm:[1,0,3,2] row_mask:0xf bank_mask:0xf bound_ctrl:1
	v_and_b32_e32 v13, 0xffff0000, v8
	v_lshlrev_b32_e32 v8, 16, v9
	v_add_f32_dpp v48, v48, v48 quad_perm:[2,3,0,1] row_mask:0xf bank_mask:0xf bound_ctrl:1
	v_and_b32_e32 v9, 0xffff0000, v9
	s_add_i32 s36, s36, 1
	v_add_f32_dpp v48, v48, v48 row_half_mirror row_mask:0xf bank_mask:0xf bound_ctrl:1
	v_fmamk_f32 v48, v48, 0x3c000000, v83
	v_rsq_f32_e32 v48, v48
	s_add_u32 s12, s12, 0x10000
	s_addc_u32 s13, s13, 0
	s_add_u32 s4, s4, 0x80
	v_pk_mul_f32 v[14:15], v[16:17], v[48:49] op_sel_hi:[1,0]
	v_pk_mul_f32 v[16:17], v[28:29], v[48:49] op_sel_hi:[1,0]
	v_pk_mul_f32 v[14:15], v[102:103], v[14:15]
	v_pk_mul_f32 v[16:17], v[98:99], v[16:17]
	v_pk_mul_f32 v[12:13], v[14:15], v[12:13]
	v_pk_mul_f32 v[14:15], v[18:19], v[48:49] op_sel_hi:[1,0]
	v_pk_mul_f32 v[18:19], v[36:37], v[48:49] op_sel_hi:[1,0]
	v_pk_mul_f32 v[14:15], v[100:101], v[14:15]
	v_pk_mul_f32 v[18:19], v[94:95], v[18:19]
	v_pk_mul_f32 v[8:9], v[14:15], v[8:9]
	v_lshlrev_b32_e32 v14, 16, v10
	v_and_b32_e32 v15, 0xffff0000, v10
	v_pk_mul_f32 v[14:15], v[16:17], v[14:15]
	v_pk_mul_f32 v[16:17], v[30:31], v[48:49] op_sel_hi:[1,0]
	v_lshlrev_b32_e32 v10, 16, v11
	v_and_b32_e32 v11, 0xffff0000, v11
	v_pk_mul_f32 v[16:17], v[96:97], v[16:17]
	v_pk_mul_f32 v[28:29], v[44:45], v[48:49] op_sel_hi:[1,0]
	v_pk_mul_f32 v[10:11], v[16:17], v[10:11]
	v_lshlrev_b32_e32 v16, 16, v4
	v_and_b32_e32 v17, 0xffff0000, v4
	v_pk_mul_f32 v[16:17], v[18:19], v[16:17]
	v_pk_mul_f32 v[18:19], v[38:39], v[48:49] op_sel_hi:[1,0]
	v_lshlrev_b32_e32 v4, 16, v5
	v_and_b32_e32 v5, 0xffff0000, v5
	v_pk_mul_f32 v[18:19], v[92:93], v[18:19]
	v_pk_mul_f32 v[28:29], v[104:105], v[28:29]
	v_pk_mul_f32 v[18:19], v[18:19], v[4:5]
	v_lshlrev_b32_e32 v4, 16, v6
	v_and_b32_e32 v5, 0xffff0000, v6
	v_pk_mul_f32 v[28:29], v[28:29], v[4:5]
	v_lshlrev_b32_e32 v4, 16, v7
	v_and_b32_e32 v5, 0xffff0000, v7
	v_pk_mul_f32 v[6:7], v[46:47], v[48:49] op_sel_hi:[1,0]
	s_addc_u32 s5, s5, 0
	v_pk_mul_f32 v[6:7], v[106:107], v[6:7]
	s_add_i32 s15, s15, 32
	v_pk_mul_f32 v[30:31], v[6:7], v[4:5]
	v_cvt_pk_bf16_f32 v5, v8, v9
	v_add_co_u32_e32 v8, vcc, s31, v78
	v_cvt_pk_bf16_f32 v4, v12, v13
	v_cvt_pk_bf16_f32 v6, v14, v15
	v_cvt_pk_bf16_f32 v7, v10, v11
	v_addc_co_u32_e32 v9, vcc, 0, v79, vcc
	global_store_dwordx4 v[8:9], v[4:7], off
	s_cmp_eq_u32 s12, 0x3d0000
	v_cvt_pk_bf16_f32 v4, v16, v17
	v_cvt_pk_bf16_f32 v5, v18, v19
	v_cvt_pk_bf16_f32 v6, v28, v29
	v_cvt_pk_bf16_f32 v7, v30, v31
	global_store_dwordx4 v[8:9], v[4:7], off offset:16
	s_waitcnt lgkmcnt(0)
	s_barrier
	s_cbranch_scc1 .LBB0_1842
	s_waitcnt vmcnt(3)
	v_mov_b64_e32 v[8:9], v[24:25]
	s_waitcnt vmcnt(2)
	v_mov_b64_e32 v[4:5], v[20:21]
	v_mov_b64_e32 v[48:49], v[64:65]
	v_mov_b64_e32 v[44:45], v[60:61]
	v_mov_b64_e32 v[36:37], v[56:57]
	v_mov_b64_e32 v[28:29], v[52:53]
	v_mov_b64_e32 v[16:17], v[40:41]
	v_mov_b64_e32 v[12:13], v[32:33]
	v_mov_b64_e32 v[10:11], v[26:27]
	v_mov_b64_e32 v[6:7], v[22:23]
	v_mov_b64_e32 v[50:51], v[66:67]
	v_mov_b64_e32 v[46:47], v[62:63]
	v_mov_b64_e32 v[38:39], v[58:59]
	v_mov_b64_e32 v[30:31], v[54:55]
	v_mov_b64_e32 v[18:19], v[42:43]
	v_mov_b64_e32 v[14:15], v[34:35]
	v_mov_b32_e32 v123, v84
	v_mov_b32_e32 v124, v85
	v_mov_b32_e32 v116, v68
	v_mov_b32_e32 v125, v86
	v_mov_b32_e32 v126, v87
	s_branch .LBB0_1838
